# plus L2 prefetch of G rows for conv-gate epilogue groups 1-3 (4 sites)
# baseline (speedup 1.0000x reference)
; __device__ __forceinline__ float row_rstd(const float* ss, int row) { return ss ? 1.0f / sqrtf(ss[row] * (1.0f / 2048.0f) + 1e-6f) : 1.0f; }
;     __device__ __forceinline__ void operator()(f32x4 (&acc)[2][2][4][2], const Unit& u, int wr, int wc, int fr, int fq) const {
;         const int row0 = u.pm * BM + wr * 64 + fr;
;         float rs[2][4];
; #pragma unroll
;         for (int ai = 0; ai < 2; ++ai)
; #pragma unroll
;             for (int m = 0; m < 4; ++m) rs[ai][m] = row_rstd(ss, row0 + ai * HALF + m * 16);
;         u32x4 own[1][4], halo[1];
;         const u32x4 z4 = {0u, 0u, 0u, 0u};
.LBB0_871:
	v_lshl_add_u32 v194, s12, 8, v217
	v_lshl_or_b32 v196, s10, 8, v219
	v_mad_i64_i32 v[198:199], s[10:11], v194, s89, 0
	v_ashrrev_i32_e32 v195, 31, v194
	v_lshl_add_u64 v[130:131], v[198:199], 1, s[34:35]
	v_ashrrev_i32_e32 v197, 31, v196
	v_lshl_add_u64 v[104:105], v[194:195], 2, s[22:23]
	v_lshl_add_u64 v[212:213], v[196:197], 1, v[130:131]
	s_mov_b32 s98, 0xffffd400
	s_mov_b32 s99, -1
	v_lshl_add_u64 v[254:255], v[212:213], 0, s[98:99]
	global_load_dword v253, v[254:255], off offset:256
	global_load_dword v253, v[212:213], off offset:256
	s_mov_b32 s98, 0x2ec00
	s_mov_b32 s99, 0
	v_lshl_add_u64 v[254:255], v[254:255], 0, s[98:99]
	global_load_dword v253, v[254:255], off offset:256
	s_mov_b32 s98, 0x2c000
	s_mov_b32 s99, 0
	v_lshl_add_u64 v[254:255], v[254:255], 0, s[98:99]
	global_load_dword v253, v[254:255], off offset:256
	s_mov_b32 s98, 0x2c000
	s_mov_b32 s99, 0
	v_lshl_add_u64 v[254:255], v[254:255], 0, s[98:99]
	global_load_dword v253, v[254:255], off offset:256
	s_mov_b32 s98, 0x2c00
	s_mov_b32 s99, 0
	v_lshl_add_u64 v[254:255], v[254:255], 0, s[98:99]
	global_load_dword v253, v[254:255], off offset:256
	s_mov_b32 s98, 0x15d400
	s_mov_b32 s99, 0
	v_lshl_add_u64 v[254:255], v[212:213], 0, s[98:99]
	global_load_dword v253, v[254:255], off
	global_load_dword v253, v[254:255], off offset:256
	s_mov_b32 s98, 0x2c00
	s_mov_b32 s99, 0
	v_lshl_add_u64 v[254:255], v[254:255], 0, s[98:99]
	global_load_dword v253, v[254:255], off
	global_load_dword v253, v[254:255], off offset:256
	s_mov_b32 s98, 0x2c000
	s_mov_b32 s99, 0
	v_lshl_add_u64 v[254:255], v[254:255], 0, s[98:99]
	global_load_dword v253, v[254:255], off
	global_load_dword v253, v[254:255], off offset:256
	s_mov_b32 s98, 0x2c000
	s_mov_b32 s99, 0
	v_lshl_add_u64 v[254:255], v[254:255], 0, s[98:99]
	global_load_dword v253, v[254:255], off
	global_load_dword v253, v[254:255], off offset:256
	s_mov_b32 s98, 0x2c000
	s_mov_b32 s99, 0
	v_lshl_add_u64 v[254:255], v[254:255], 0, s[98:99]
	global_load_dword v253, v[254:255], off
	global_load_dword v253, v[254:255], off offset:256
	s_mov_b32 s98, 0x2c00
	s_mov_b32 s99, 0
	v_lshl_add_u64 v[254:255], v[254:255], 0, s[98:99]
	global_load_dword v253, v[254:255], off
	global_load_dword v253, v[254:255], off offset:256
	global_load_dword v204, v[104:105], off offset:192
	global_load_dword v231, v[104:105], off offset:512
	global_load_dword v230, v[104:105], off offset:576
	global_load_dword v229, v[104:105], off offset:640
	global_load_dword v228, v[104:105], off offset:704
	global_load_dword v207, v[104:105], off
	global_load_dword v206, v[104:105], off offset:64
	global_load_dword v205, v[104:105], off offset:128
	global_load_dwordx4 v[178:181], v[212:213], off
	v_add_co_u32_e32 v104, vcc, s90, v212
	v_and_b32_e32 v195, 0x7cf, v194
	s_nop 0
	v_addc_co_u32_e32 v105, vcc, 0, v213, vcc
	v_add_co_u32_e32 v130, vcc, 0x58000, v212
	s_mov_b64 s[10:11], 0
	s_nop 0
	v_addc_co_u32_e32 v131, vcc, 0, v213, vcc
	global_load_dwordx4 v[174:177], v[104:105], off
	global_load_dwordx4 v[146:149], v[130:131], off
	v_add_co_u32_e32 v104, vcc, 0x84000, v212
	v_cmp_ne_u32_e64 s[12:13], s91, v195
	s_nop 0
	v_addc_co_u32_e32 v105, vcc, 0, v213, vcc
	global_load_dwordx4 v[130:133], v[104:105], off
	v_cmp_lt_i32_e32 vcc, 14, v216
	s_and_saveexec_b64 s[14:15], vcc
	s_xor_b64 s[14:15], exec, s[14:15]
	s_and_b64 s[10:11], s[12:13], exec
	s_or_saveexec_b64 s[14:15], s[14:15]
	v_mov_b64_e32 v[104:105], 0x86c00
	s_xor_b64 exec, exec, s[14:15]
	s_cbranch_execz .LBB0_877
	v_cmp_eq_u32_e32 vcc, 0, v216
	s_mov_b64 s[18:19], s[10:11]
	s_and_saveexec_b64 s[20:21], vcc
	v_cmp_ne_u32_e32 vcc, 0, v195
	s_andn2_b64 s[18:19], s[10:11], exec
	s_and_b64 s[64:65], vcc, exec
	s_or_b64 s[18:19], s[18:19], s[64:65]
	s_or_b64 exec, exec, s[20:21]
	v_mov_b32_e32 v104, 0xffffd400
	s_andn2_b64 s[10:11], s[10:11], exec
	s_and_b64 s[18:19], s[18:19], exec
	v_mov_b32_e32 v105, -1
	s_or_b64 s[10:11], s[10:11], s[18:19]

; __device__ __forceinline__ float row_rstd(const float* ss, int row) { return ss ? 1.0f / sqrtf(ss[row] * (1.0f / 2048.0f) + 1e-6f) : 1.0f; }
;     __device__ __forceinline__ void operator()(f32x4 (&acc)[2][2][4][2], const Unit& u, int wr, int wc, int fr, int fq) const {
;         const int row0 = u.pm * BM + wr * 64 + fr;
;         float rs[2][4];
; #pragma unroll
;         for (int ai = 0; ai < 2; ++ai)
; #pragma unroll
;             for (int m = 0; m < 4; ++m) rs[ai][m] = row_rstd(ss, row0 + ai * HALF + m * 16);
;         u32x4 own[1][4], halo[1];
;         const u32x4 z4 = {0u, 0u, 0u, 0u};
.LBB0_1037:
	v_lshl_add_u32 v196, s14, 8, v224
	v_lshl_or_b32 v198, s12, 8, v226
	v_mad_i64_i32 v[200:201], s[12:13], v196, s84, 0
	v_ashrrev_i32_e32 v197, 31, v196
	v_lshl_add_u64 v[130:131], v[200:201], 1, s[28:29]
	v_ashrrev_i32_e32 v199, 31, v198
	v_lshl_add_u64 v[128:129], v[196:197], 2, s[34:35]
	v_lshl_add_u64 v[214:215], v[198:199], 1, v[130:131]
	s_mov_b32 s98, 0xffffd400
	s_mov_b32 s99, -1
	v_lshl_add_u64 v[254:255], v[214:215], 0, s[98:99]
	global_load_dword v253, v[254:255], off offset:256
	global_load_dword v253, v[214:215], off offset:256
	s_mov_b32 s98, 0x2ec00
	s_mov_b32 s99, 0
	v_lshl_add_u64 v[254:255], v[254:255], 0, s[98:99]
	global_load_dword v253, v[254:255], off offset:256
	s_mov_b32 s98, 0x2c000
	s_mov_b32 s99, 0
	v_lshl_add_u64 v[254:255], v[254:255], 0, s[98:99]
	global_load_dword v253, v[254:255], off offset:256
	s_mov_b32 s98, 0x2c000
	s_mov_b32 s99, 0
	v_lshl_add_u64 v[254:255], v[254:255], 0, s[98:99]
	global_load_dword v253, v[254:255], off offset:256
	s_mov_b32 s98, 0x2c00
	s_mov_b32 s99, 0
	v_lshl_add_u64 v[254:255], v[254:255], 0, s[98:99]
	global_load_dword v253, v[254:255], off offset:256
	s_mov_b32 s98, 0x15d400
	s_mov_b32 s99, 0
	v_lshl_add_u64 v[254:255], v[214:215], 0, s[98:99]
	global_load_dword v253, v[254:255], off
	global_load_dword v253, v[254:255], off offset:256
	s_mov_b32 s98, 0x2c00
	s_mov_b32 s99, 0
	v_lshl_add_u64 v[254:255], v[254:255], 0, s[98:99]
	global_load_dword v253, v[254:255], off
	global_load_dword v253, v[254:255], off offset:256
	s_mov_b32 s98, 0x2c000
	s_mov_b32 s99, 0
	v_lshl_add_u64 v[254:255], v[254:255], 0, s[98:99]
	global_load_dword v253, v[254:255], off
	global_load_dword v253, v[254:255], off offset:256
	s_mov_b32 s98, 0x2c000
	s_mov_b32 s99, 0
	v_lshl_add_u64 v[254:255], v[254:255], 0, s[98:99]
	global_load_dword v253, v[254:255], off
	global_load_dword v253, v[254:255], off offset:256
	s_mov_b32 s98, 0x2c000
	s_mov_b32 s99, 0
	v_lshl_add_u64 v[254:255], v[254:255], 0, s[98:99]
	global_load_dword v253, v[254:255], off
	global_load_dword v253, v[254:255], off offset:256
	s_mov_b32 s98, 0x2c00
	s_mov_b32 s99, 0
	v_lshl_add_u64 v[254:255], v[254:255], 0, s[98:99]
	global_load_dword v253, v[254:255], off
	global_load_dword v253, v[254:255], off offset:256
	global_load_dword v206, v[128:129], off offset:192
	global_load_dword v235, v[128:129], off offset:512
	global_load_dword v234, v[128:129], off offset:576
	global_load_dword v233, v[128:129], off offset:640
	global_load_dword v232, v[128:129], off offset:704
	global_load_dword v144, v[128:129], off
	global_load_dword v143, v[128:129], off offset:64
	global_load_dword v142, v[128:129], off offset:128
	global_load_dwordx4 v[176:179], v[214:215], off
	v_add_co_u32_e32 v128, vcc, s85, v214
	v_and_b32_e32 v197, 0x7cf, v196
	s_nop 0
	v_addc_co_u32_e32 v129, vcc, 0, v215, vcc
	v_add_co_u32_e32 v130, vcc, 0x58000, v214
	s_mov_b64 s[14:15], 0
	s_nop 0
	v_addc_co_u32_e32 v131, vcc, 0, v215, vcc
	global_load_dwordx4 v[156:159], v[128:129], off
	global_load_dwordx4 v[132:135], v[130:131], off
	v_add_co_u32_e32 v128, vcc, 0x84000, v214
	v_cmp_ne_u32_e64 s[12:13], s86, v197
	s_nop 0
	v_addc_co_u32_e32 v129, vcc, 0, v215, vcc
	global_load_dwordx4 v[128:131], v[128:129], off
	v_cmp_lt_i32_e32 vcc, 14, v223
	s_and_saveexec_b64 s[18:19], vcc
	s_xor_b64 s[18:19], exec, s[18:19]
	s_and_b64 s[14:15], s[12:13], exec
	s_or_saveexec_b64 s[18:19], s[18:19]
	v_mov_b64_e32 v[140:141], 0x86c00
	s_xor_b64 exec, exec, s[18:19]
	s_cbranch_execz .LBB0_1043
	v_cmp_eq_u32_e32 vcc, 0, v223
	s_mov_b64 s[20:21], s[14:15]
	s_and_saveexec_b64 s[58:59], vcc
	v_cmp_ne_u32_e32 vcc, 0, v197
	s_andn2_b64 s[20:21], s[14:15], exec
	s_and_b64 s[60:61], vcc, exec
	s_or_b64 s[20:21], s[20:21], s[60:61]
	s_or_b64 exec, exec, s[58:59]
	v_mov_b32_e32 v140, 0xffffd400
	s_andn2_b64 s[14:15], s[14:15], exec
	s_and_b64 s[20:21], s[20:21], exec
	v_mov_b32_e32 v141, -1
	s_or_b64 s[14:15], s[14:15], s[20:21]

; __device__ __forceinline__ float row_rstd(const float* ss, int row) { return ss ? 1.0f / sqrtf(ss[row] * (1.0f / 2048.0f) + 1e-6f) : 1.0f; }
;     __device__ __forceinline__ void operator()(f32x4 (&acc)[2][2][4][2], const Unit& u, int wr, int wc, int fr, int fq) const {
;         const int row0 = u.pm * BM + wr * 64 + fr;
;         float rs[2][4];
; #pragma unroll
;         for (int ai = 0; ai < 2; ++ai)
; #pragma unroll
;             for (int m = 0; m < 4; ++m) rs[ai][m] = row_rstd(ss, row0 + ai * HALF + m * 16);
;         u32x4 own[1][4], halo[1];
;         const u32x4 z4 = {0u, 0u, 0u, 0u};
.LBB0_1652:
	v_lshl_add_u32 v192, s10, 8, v217
	v_lshl_or_b32 v194, s6, 8, v219
	v_mad_i64_i32 v[196:197], s[6:7], v192, s78, 0
	v_ashrrev_i32_e32 v193, 31, v192
	v_lshl_add_u64 v[130:131], v[196:197], 1, s[24:25]
	v_ashrrev_i32_e32 v195, 31, v194
	v_lshl_add_u64 v[128:129], v[192:193], 2, s[18:19]
	v_lshl_add_u64 v[206:207], v[194:195], 1, v[130:131]
	s_mov_b32 s98, 0xffffd400
	s_mov_b32 s99, -1
	v_lshl_add_u64 v[254:255], v[206:207], 0, s[98:99]
	global_load_dword v253, v[254:255], off offset:256
	global_load_dword v253, v[206:207], off offset:256
	s_mov_b32 s98, 0x2ec00
	s_mov_b32 s99, 0
	v_lshl_add_u64 v[254:255], v[254:255], 0, s[98:99]
	global_load_dword v253, v[254:255], off offset:256
	s_mov_b32 s98, 0x2c000
	s_mov_b32 s99, 0
	v_lshl_add_u64 v[254:255], v[254:255], 0, s[98:99]
	global_load_dword v253, v[254:255], off offset:256
	s_mov_b32 s98, 0x2c000
	s_mov_b32 s99, 0
	v_lshl_add_u64 v[254:255], v[254:255], 0, s[98:99]
	global_load_dword v253, v[254:255], off offset:256
	s_mov_b32 s98, 0x2c00
	s_mov_b32 s99, 0
	v_lshl_add_u64 v[254:255], v[254:255], 0, s[98:99]
	global_load_dword v253, v[254:255], off offset:256
	s_mov_b32 s98, 0x15d400
	s_mov_b32 s99, 0
	v_lshl_add_u64 v[254:255], v[206:207], 0, s[98:99]
	global_load_dword v253, v[254:255], off
	global_load_dword v253, v[254:255], off offset:256
	s_mov_b32 s98, 0x2c00
	s_mov_b32 s99, 0
	v_lshl_add_u64 v[254:255], v[254:255], 0, s[98:99]
	global_load_dword v253, v[254:255], off
	global_load_dword v253, v[254:255], off offset:256
	s_mov_b32 s98, 0x2c000
	s_mov_b32 s99, 0
	v_lshl_add_u64 v[254:255], v[254:255], 0, s[98:99]
	global_load_dword v253, v[254:255], off
	global_load_dword v253, v[254:255], off offset:256
	s_mov_b32 s98, 0x2c000
	s_mov_b32 s99, 0
	v_lshl_add_u64 v[254:255], v[254:255], 0, s[98:99]
	global_load_dword v253, v[254:255], off
	global_load_dword v253, v[254:255], off offset:256
	s_mov_b32 s98, 0x2c000
	s_mov_b32 s99, 0
	v_lshl_add_u64 v[254:255], v[254:255], 0, s[98:99]
	global_load_dword v253, v[254:255], off
	global_load_dword v253, v[254:255], off offset:256
	s_mov_b32 s98, 0x2c00
	s_mov_b32 s99, 0
	v_lshl_add_u64 v[254:255], v[254:255], 0, s[98:99]
	global_load_dword v253, v[254:255], off
	global_load_dword v253, v[254:255], off offset:256
	global_load_dword v198, v[128:129], off offset:192
	global_load_dword v229, v[128:129], off offset:512
	global_load_dword v228, v[128:129], off offset:576
	global_load_dword v227, v[128:129], off offset:640
	global_load_dword v226, v[128:129], off offset:704
	global_load_dword v144, v[128:129], off
	global_load_dword v143, v[128:129], off offset:64
	global_load_dword v142, v[128:129], off offset:128
	global_load_dwordx4 v[176:179], v[206:207], off
	v_add_co_u32_e32 v128, vcc, s79, v206
	v_and_b32_e32 v193, 0x7cf, v192
	s_nop 0
	v_addc_co_u32_e32 v129, vcc, 0, v207, vcc
	v_add_co_u32_e32 v130, vcc, 0x58000, v206
	s_mov_b64 s[10:11], 0
	s_nop 0
	v_addc_co_u32_e32 v131, vcc, 0, v207, vcc
	global_load_dwordx4 v[156:159], v[128:129], off
	global_load_dwordx4 v[132:135], v[130:131], off
	v_add_co_u32_e32 v128, vcc, 0x84000, v206
	v_cmp_ne_u32_e64 s[6:7], s80, v193
	s_nop 0
	v_addc_co_u32_e32 v129, vcc, 0, v207, vcc
	global_load_dwordx4 v[128:131], v[128:129], off
	v_cmp_lt_i32_e32 vcc, 14, v216
	s_and_saveexec_b64 s[12:13], vcc
	s_xor_b64 s[12:13], exec, s[12:13]
	s_and_b64 s[10:11], s[6:7], exec
	s_or_saveexec_b64 s[12:13], s[12:13]
	v_mov_b64_e32 v[140:141], 0x86c00
	s_xor_b64 exec, exec, s[12:13]
	s_cbranch_execz .LBB0_1658
	v_cmp_eq_u32_e32 vcc, 0, v216
	s_mov_b64 s[14:15], s[10:11]
	s_and_saveexec_b64 s[56:57], vcc
	v_cmp_ne_u32_e32 vcc, 0, v193
	s_andn2_b64 s[14:15], s[10:11], exec
	s_and_b64 s[58:59], vcc, exec
	s_or_b64 s[14:15], s[14:15], s[58:59]
	s_or_b64 exec, exec, s[56:57]
	v_mov_b32_e32 v140, 0xffffd400
	s_andn2_b64 s[10:11], s[10:11], exec
	s_and_b64 s[14:15], s[14:15], exec
	v_mov_b32_e32 v141, -1
	s_or_b64 s[10:11], s[10:11], s[14:15]

; __device__ __forceinline__ float row_rstd(const float* ss, int row) { return ss ? 1.0f / sqrtf(ss[row] * (1.0f / 2048.0f) + 1e-6f) : 1.0f; }
;     __device__ __forceinline__ void operator()(f32x4 (&acc)[2][2][4][2], const Unit& u, int wr, int wc, int fr, int fq) const {
;         const int row0 = u.pm * BM + wr * 64 + fr;
;         float rs[2][4];
; #pragma unroll
;         for (int ai = 0; ai < 2; ++ai)
; #pragma unroll
;             for (int m = 0; m < 4; ++m) rs[ai][m] = row_rstd(ss, row0 + ai * HALF + m * 16);
;         u32x4 own[1][4], halo[1];
;         const u32x4 z4 = {0u, 0u, 0u, 0u};
.LBB0_1798:
	v_lshl_add_u32 v196, s14, 8, v222
	v_lshl_or_b32 v198, s12, 8, v224
	v_mad_i64_i32 v[200:201], s[8:9], v196, s74, 0
	v_ashrrev_i32_e32 v197, 31, v196
	v_lshl_add_u64 v[130:131], v[200:201], 1, s[20:21]
	v_ashrrev_i32_e32 v199, 31, v198
	v_lshl_add_u64 v[128:129], v[196:197], 2, s[28:29]
	v_lshl_add_u64 v[210:211], v[198:199], 1, v[130:131]
	s_mov_b32 s98, 0xffffd400
	s_mov_b32 s99, -1
	v_lshl_add_u64 v[254:255], v[210:211], 0, s[98:99]
	global_load_dword v253, v[254:255], off offset:256
	global_load_dword v253, v[210:211], off offset:256
	s_mov_b32 s98, 0x2ec00
	s_mov_b32 s99, 0
	v_lshl_add_u64 v[254:255], v[254:255], 0, s[98:99]
	global_load_dword v253, v[254:255], off offset:256
	s_mov_b32 s98, 0x2c000
	s_mov_b32 s99, 0
	v_lshl_add_u64 v[254:255], v[254:255], 0, s[98:99]
	global_load_dword v253, v[254:255], off offset:256
	s_mov_b32 s98, 0x2c000
	s_mov_b32 s99, 0
	v_lshl_add_u64 v[254:255], v[254:255], 0, s[98:99]
	global_load_dword v253, v[254:255], off offset:256
	s_mov_b32 s98, 0x2c00
	s_mov_b32 s99, 0
	v_lshl_add_u64 v[254:255], v[254:255], 0, s[98:99]
	global_load_dword v253, v[254:255], off offset:256
	s_mov_b32 s98, 0x15d400
	s_mov_b32 s99, 0
	v_lshl_add_u64 v[254:255], v[210:211], 0, s[98:99]
	global_load_dword v253, v[254:255], off
	global_load_dword v253, v[254:255], off offset:256
	s_mov_b32 s98, 0x2c00
	s_mov_b32 s99, 0
	v_lshl_add_u64 v[254:255], v[254:255], 0, s[98:99]
	global_load_dword v253, v[254:255], off
	global_load_dword v253, v[254:255], off offset:256
	s_mov_b32 s98, 0x2c000
	s_mov_b32 s99, 0
	v_lshl_add_u64 v[254:255], v[254:255], 0, s[98:99]
	global_load_dword v253, v[254:255], off
	global_load_dword v253, v[254:255], off offset:256
	s_mov_b32 s98, 0x2c000
	s_mov_b32 s99, 0
	v_lshl_add_u64 v[254:255], v[254:255], 0, s[98:99]
	global_load_dword v253, v[254:255], off
	global_load_dword v253, v[254:255], off offset:256
	s_mov_b32 s98, 0x2c000
	s_mov_b32 s99, 0
	v_lshl_add_u64 v[254:255], v[254:255], 0, s[98:99]
	global_load_dword v253, v[254:255], off
	global_load_dword v253, v[254:255], off offset:256
	s_mov_b32 s98, 0x2c00
	s_mov_b32 s99, 0
	v_lshl_add_u64 v[254:255], v[254:255], 0, s[98:99]
	global_load_dword v253, v[254:255], off
	global_load_dword v253, v[254:255], off offset:256
	global_load_dword v202, v[128:129], off offset:192
	global_load_dword v233, v[128:129], off offset:512
	global_load_dword v232, v[128:129], off offset:576
	global_load_dword v231, v[128:129], off offset:640
	global_load_dword v230, v[128:129], off offset:704
	global_load_dword v144, v[128:129], off
	global_load_dword v143, v[128:129], off offset:64
	global_load_dword v142, v[128:129], off offset:128
	global_load_dwordx4 v[176:179], v[210:211], off
	v_add_co_u32_e32 v128, vcc, s75, v210
	v_and_b32_e32 v197, 0x7cf, v196
	s_nop 0
	v_addc_co_u32_e32 v129, vcc, 0, v211, vcc
	v_add_co_u32_e32 v130, vcc, 0x58000, v210
	s_mov_b64 s[10:11], 0
	s_nop 0
	v_addc_co_u32_e32 v131, vcc, 0, v211, vcc
	global_load_dwordx4 v[156:159], v[128:129], off
	global_load_dwordx4 v[132:135], v[130:131], off
	v_add_co_u32_e32 v128, vcc, 0x84000, v210
	v_cmp_ne_u32_e64 s[8:9], s76, v197
	s_nop 0
	v_addc_co_u32_e32 v129, vcc, 0, v211, vcc
	global_load_dwordx4 v[128:131], v[128:129], off
	v_cmp_lt_i32_e32 vcc, 14, v221
	s_and_saveexec_b64 s[12:13], vcc
	s_xor_b64 s[12:13], exec, s[12:13]
	s_and_b64 s[10:11], s[8:9], exec
	s_or_saveexec_b64 s[12:13], s[12:13]
	v_mov_b64_e32 v[140:141], 0x86c00
	s_xor_b64 exec, exec, s[12:13]
	s_cbranch_execz .LBB0_1804
	v_cmp_eq_u32_e32 vcc, 0, v221
	s_mov_b64 s[14:15], s[10:11]
	s_and_saveexec_b64 s[52:53], vcc
	v_cmp_ne_u32_e32 vcc, 0, v197
	s_andn2_b64 s[14:15], s[10:11], exec
	s_and_b64 s[54:55], vcc, exec
	s_or_b64 s[14:15], s[14:15], s[54:55]
	s_or_b64 exec, exec, s[52:53]
	v_mov_b32_e32 v140, 0xffffd400
	s_andn2_b64 s[10:11], s[10:11], exec
	s_and_b64 s[14:15], s[14:15], exec
	v_mov_b32_e32 v141, -1
	s_or_b64 s[10:11], s[10:11], s[14:15]

; __global__ void __launch_bounds__(NTHREADS, 2) fwd_megakernel(Args a) {
	.amdhsa_kernel _Z14fwd_megakernel4Args
		.amdhsa_group_segment_fixed_size 0
		.amdhsa_private_segment_fixed_size 0
		.amdhsa_kernarg_size 504
		.amdhsa_user_sgpr_count 2
		.amdhsa_user_sgpr_dispatch_ptr 0
		.amdhsa_user_sgpr_queue_ptr 0
		.amdhsa_user_sgpr_kernarg_segment_ptr 1
		.amdhsa_user_sgpr_dispatch_id 0
		.amdhsa_user_sgpr_kernarg_preload_length 0
		.amdhsa_user_sgpr_kernarg_preload_offset 0
		.amdhsa_user_sgpr_private_segment_size 0
		.amdhsa_uses_dynamic_stack 0
		.amdhsa_enable_private_segment 0
		.amdhsa_system_sgpr_workgroup_id_x 1
		.amdhsa_system_sgpr_workgroup_id_y 0
		.amdhsa_system_sgpr_workgroup_id_z 0
		.amdhsa_system_sgpr_workgroup_info 0
		.amdhsa_system_vgpr_workitem_id 2
		.amdhsa_next_free_vgpr 256
		.amdhsa_next_free_sgpr 102
		.amdhsa_accum_offset 256
		.amdhsa_reserve_vcc 1
		.amdhsa_float_round_mode_32 0
		.amdhsa_float_round_mode_16_64 0
		.amdhsa_float_denorm_mode_32 3
		.amdhsa_float_denorm_mode_16_64 3
		.amdhsa_dx10_clamp 1
		.amdhsa_ieee_mode 1
		.amdhsa_fp16_overflow 0
		.amdhsa_tg_split 0
		.amdhsa_exception_fp_ieee_invalid_op 0
		.amdhsa_exception_fp_denorm_src 0
		.amdhsa_exception_fp_ieee_div_zero 0
		.amdhsa_exception_fp_ieee_overflow 0
		.amdhsa_exception_fp_ieee_underflow 0
		.amdhsa_exception_fp_ieee_inexact 0
		.amdhsa_exception_int_div_zero 0
	.end_amdhsa_kernel

; __global__ void __launch_bounds__(NTHREADS, 2) fwd_megakernel(Args a) {
.Lfunc_end0:
	.size	_Z14fwd_megakernel4Args, .Lfunc_end0-_Z14fwd_megakernel4Args
	.set _Z14fwd_megakernel4Args.num_vgpr, 256
	.set _Z14fwd_megakernel4Args.num_agpr, 0
	.set _Z14fwd_megakernel4Args.numbered_sgpr, 102
	.set _Z14fwd_megakernel4Args.num_named_barrier, 0
	.set _Z14fwd_megakernel4Args.private_seg_size, 0
	.set _Z14fwd_megakernel4Args.uses_vcc, 1
	.set _Z14fwd_megakernel4Args.uses_flat_scratch, 0
	.set _Z14fwd_megakernel4Args.has_dyn_sized_stack, 0
	.set _Z14fwd_megakernel4Args.has_recursion, 0
	.set _Z14fwd_megakernel4Args.has_indirect_call, 0

; __global__ void __launch_bounds__(NTHREADS, 2) fwd_megakernel(Args a) {
amdhsa.kernels:
  - .agpr_count:     0
    .args:
      - .offset:         0
        .size:           248
        .value_kind:     by_value
      - .offset:         248
        .size:           4
        .value_kind:     hidden_block_count_x
      - .offset:         252
        .size:           4
        .value_kind:     hidden_block_count_y
      - .offset:         256
        .size:           4
        .value_kind:     hidden_block_count_z
      - .offset:         260
        .size:           2
        .value_kind:     hidden_group_size_x
      - .offset:         262
        .size:           2
        .value_kind:     hidden_group_size_y
      - .offset:         264
        .size:           2
        .value_kind:     hidden_group_size_z
      - .offset:         266
        .size:           2
        .value_kind:     hidden_remainder_x
      - .offset:         268
        .size:           2
        .value_kind:     hidden_remainder_y
      - .offset:         270
        .size:           2
        .value_kind:     hidden_remainder_z
      - .offset:         288
        .size:           8
        .value_kind:     hidden_global_offset_x
      - .offset:         296
        .size:           8
        .value_kind:     hidden_global_offset_y
      - .offset:         304
        .size:           8
        .value_kind:     hidden_global_offset_z
      - .offset:         312
        .size:           2
        .value_kind:     hidden_grid_dims
      - .offset:         336
        .size:           8
        .value_kind:     hidden_multigrid_sync_arg
      - .offset:         368
        .size:           4
        .value_kind:     hidden_dynamic_lds_size
    .group_segment_fixed_size: 0
    .kernarg_segment_align: 8
    .kernarg_segment_size: 504
    .language:       OpenCL C
    .language_version:
      - 2
      - 0
    .max_flat_workgroup_size: 512
    .name:           _Z14fwd_megakernel4Args
    .private_segment_fixed_size: 0
    .sgpr_count:     108
    .sgpr_spill_count: 0
    .symbol:         _Z14fwd_megakernel4Args.kd
    .uniform_work_group_size: 1
    .uses_dynamic_stack: false
    .vgpr_count:     256
    .vgpr_spill_count: 0
    .wavefront_size: 64
